# FoX unit loop: norm-maxima loads issued right after the unit id is known, next unit's queue ticket prefetched during the prologue (no blocking atomic per unit)
# baseline (speedup 1.0000x reference)
; __device__ __forceinline__ int lane_id() { unsigned m = ~0u; asm volatile("" : "+s"(m)); return (int)__builtin_amdgcn_mbcnt_hi(m, __builtin_amdgcn_mbcnt_lo(m, 0u)); }
; #define LAS __attribute__((address_space(3)))
; template <int li> __device__ __forceinline__ void layer_fwd(const Args& args, LAS unsigned char* lds, const int wid_s) {
;     ...
;             if (fox) {
;                 unsigned* qctr = (unsigned*)ws + 24576 + j;
;                 LAS unsigned* uq = (LAS unsigned*)(lds + att::LDS_SC + 64);
;                 const float bmax = 0.f;
; #pragma unroll 1
;                 for (;;) {
;                     int zl = 0; asm volatile("" : "+v"(zl));
;                     if ((wid_s == 0) && (pg8::lane_id() == 0)) uq[zl] = atomicAdd(qctr, 1u);
;                     __syncthreads();
;                     const unsigned u = (unsigned)__builtin_amdgcn_readfirstlane((int)uq[zl]);
.LBB0_363:
	s_or_b64 exec, exec, s[6:7]
	s_mov_b32 s6, -1
	s_waitcnt lgkmcnt(0)
	s_barrier
	s_mov_b32 s8, 0
	v_mbcnt_lo_u32_b32 v0, s6, 0
	v_mbcnt_hi_u32_b32 v0, s6, v0
	s_mov_b32 s6, s2
	s_load_dwordx2 s[6:7], s[0:1], 0x88
	s_ashr_i32 s9, s8, 31
	s_mov_b32 s28, 0xfffe0000
	s_mov_b32 s13, 0
	v_mov_b32_e32 v119, 0
	s_waitcnt lgkmcnt(0)
	s_add_u32 s6, s6, s8
	s_addc_u32 s7, s7, s9
	s_add_u32 s14, s6, 0x200000
	s_addc_u32 s15, s7, 0
	s_add_u32 s25, s6, 0x9400000
	s_addc_u32 s36, s7, 0
	s_add_u32 s37, s6, 0xb400000
	s_addc_u32 s40, s7, 0
	s_add_u32 s41, s6, 0xd400000
	s_addc_u32 s44, s7, 0
	s_add_u32 s18, s6, 0x8000
	s_addc_u32 s19, s7, 0
	s_add_u32 s20, s6, 0xa000
	s_addc_u32 s21, s7, 0
	s_add_u32 s22, s6, 0x18000
	s_addc_u32 s23, s7, 0
	s_lshl_b32 s92, s3, 4
	s_add_i32 s74, s68, 0
	s_lshl_b32 s78, s3, 5
	s_lshl_b32 s57, s3, 3
	s_and_b32 s79, s92, 48
	s_lshl_b32 s56, s66, 5
	s_add_i32 s75, s74, 0x8000
	s_cmp_eq_u32 s66, 1
	s_cselect_b64 s[10:11], -1, 0
	s_cmpk_lt_u32 s93, 0x100
	s_cselect_b64 s[16:17], -1, 0
	s_lshl_b32 s6, s3, 8
	s_add_i32 s97, s6, 0
	s_lshl_b32 s6, s3, 12
	s_add_i32 s81, s6, 0
	s_add_i32 s80, s97, 0x10000
	s_add_i32 s81, s81, 0x10800
	s_movk_i32 s45, 0x80
	s_add_i32 s46, 0, 0x1dc04
	s_add_i32 s47, 0, 0x1dc08
	s_add_i32 s48, 0, 0x1dc0c
	s_add_i32 s49, 0, 0x1dc10
	s_add_i32 s50, 0, 0x1dc14
	s_add_i32 s51, 0, 0x1dc18
	s_mov_b32 s24, 0x3fb8aa3b
	s_mov_b32 s52, 0xf800000
	v_mov_b32_e32 v124, 0x260
	s_mov_b32 s53, 0xc3200000
	v_mov_b32_e32 v125, 0xc2800000
	s_mov_b64 s[26:27], 0x780000
	s_add_i32 s85, 0, 0x1c600
	s_mov_b32 s29, -1
	v_bfrev_b32_e32 v126, 0.5
	v_mov_b32_e32 v127, 0xff800000
	s_and_b64 vcc, exec, s[4:5]
	s_cbranch_vccnz fxq0_pre
	s_mov_b64 s[6:7], exec
	s_mov_b64 exec, 1
	v_mov_b32_e32 v2, 1
	global_atomic_add v2, v119, v2, s[22:23] sc0
	v_mov_b32_e32 v3, 0x1dc40
	s_waitcnt vmcnt(0)
	ds_write_b32 v3, v2
	s_mov_b64 exec, s[6:7]
fxq0_pre:
	s_branch .LBB0_366

; __device__ __forceinline__ int lane_id() { unsigned m = ~0u; asm volatile("" : "+s"(m)); return (int)__builtin_amdgcn_mbcnt_hi(m, __builtin_amdgcn_mbcnt_lo(m, 0u)); }
; #define LAS __attribute__((address_space(3)))
; template <int li> __device__ __forceinline__ void layer_fwd(const Args& args, LAS unsigned char* lds, const int wid_s) {
;     ...
;                 for (;;) {
;                     int zl = 0; asm volatile("" : "+v"(zl));
;                     if ((wid_s == 0) && (pg8::lane_id() == 0)) uq[zl] = atomicAdd(qctr, 1u);
;                     __syncthreads();
;                     const unsigned u = (unsigned)__builtin_amdgcn_readfirstlane((int)uq[zl]);
;                     if (u >= 1024u) break;
;                     const int qb = 15 - (int)(u >> 6), bh = (int)(u & 63u), b = bh >> 4, h = bh & 15;
;                     const int lnl = pg8::lane_id(); const int tdl = wid_s * 64 + lnl;
;                     const int L = 256 * (qb + 1);
;                     float v[8];
;                     if (8 * tdl < L) { const float* lf = logf_buf + (size_t)bh * SEQ + 8 * tdl; const f32x4 a = *(const f32x4*)lf, c = *(const f32x4*)(lf + 4);
;                         v[0] = a[0]; v[1] = v[0] + a[1]; v[2] = v[1] + a[2]; v[3] = v[2] + a[3]; v[4] = v[3] + c[0]; v[5] = v[4] + c[1]; v[6] = v[5] + c[2]; v[7] = v[6] + c[3]; }
;                     else {
; #pragma unroll
;                         for (int e = 0; e < 8; ++e) v[e] = 0.f; }
;                     float incl = v[7];
; #pragma unroll
;                     for (int o = 1; o < 64; o <<= 1) { const float t = __int_as_float(__builtin_amdgcn_ds_bpermute(((lnl - o) & 63) << 2, __float_as_int(incl))); if (lnl >= o) incl += t; }
;                     LAS float* wsum = (LAS float*)(lds + att::LDS_SC);
;                     if (lnl == 63) wsum[tdl >> 6] = incl;
;                     __syncthreads();
;                     float basev = incl - v[7];
.LBB0_366:
	v_mov_b32_e32 v0, 0
	v_lshl_add_u32 v0, v0, 2, 0
	v_add_u32_e32 v0, 0x1dc40, v0
	s_waitcnt lgkmcnt(0)
	s_barrier
	ds_read_b32 v0, v0
	s_mov_b64 s[6:7], -1
	s_waitcnt lgkmcnt(0)
	v_readfirstlane_b32 s12, v0
	s_cmpk_gt_u32 s12, 0x3ff
	s_cbranch_scc1 .LBB0_365
	s_and_b32 s8, s12, 63
	s_lshr_b32 s9, s12, 6
	s_sub_i32 s9, 15, s9
	s_lshl_b32 s9, s9, 3
	s_lshl_b32 s6, s8, 7
	s_or_b32 s9, s9, s6
	s_lshl_b32 s8, s8, 3
	v_mov_b32_e32 v106, s8
	v_mov_b32_e32 v107, s9
	s_and_b64 vcc, exec, s[4:5]
	s_cbranch_vccnz fxq0_noq
	s_mov_b64 s[6:7], exec
	s_mov_b64 exec, 1
	v_mov_b32_e32 v108, 1
	global_atomic_add v108, v119, v108, s[22:23] sc0
	s_mov_b64 exec, s[6:7]
fxq0_noq:
	global_load_dwordx2 v[102:103], v106, s[20:21]
	global_load_dwordx2 v[104:105], v107, s[18:19]
	s_mov_b32 s6, -1
	s_lshr_b32 s54, s12, 6
	v_mbcnt_lo_u32_b32 v0, s6, 0
	v_mbcnt_hi_u32_b32 v10, s6, v0
	v_add_u32_e32 v11, s77, v10
	s_lshl_b32 s6, s54, 8
	s_sub_i32 s6, 0x1000, s6
	v_lshlrev_b32_e32 v4, 3, v11
	v_mov_b32_e32 v0, 0
	s_and_b32 s30, s12, 63
	v_cmp_gt_i32_e32 vcc, s6, v4
	v_mov_b32_e32 v1, v0
	v_mov_b32_e32 v8, v0
	v_mov_b32_e32 v9, v0
	v_mov_b32_e32 v6, v0
	v_mov_b32_e32 v7, v0
	v_mov_b32_e32 v2, v0
	v_mov_b32_e32 v3, v0
	s_and_saveexec_b64 s[6:7], vcc
	s_cbranch_execz .LBB0_375
	s_lshl_b32 s8, s30, 14
	s_add_u32 s8, s14, s8
	s_addc_u32 s9, s15, 0
	v_ashrrev_i32_e32 v5, 31, v4
	v_lshl_add_u64 v[6:7], v[4:5], 2, s[8:9]
	global_load_dwordx4 v[0:3], v[6:7], off
	global_load_dwordx4 v[12:15], v[6:7], off offset:16
	s_waitcnt vmcnt(1)
	v_add_f32_e32 v1, v0, v1
	v_add_f32_e32 v8, v2, v1
	v_add_f32_e32 v9, v3, v8
	s_waitcnt vmcnt(0)
	v_add_f32_e32 v6, v12, v9
	v_add_f32_e32 v7, v13, v6
	v_add_f32_e32 v2, v14, v7
	v_add_f32_e32 v3, v15, v2
.LBB0_375:
	s_or_b64 exec, exec, s[6:7]
	v_lshlrev_b32_e32 v5, 2, v10
	v_add_u32_e32 v12, 0xfc, v5
	v_and_b32_e32 v12, 0xfc, v12
	ds_bpermute_b32 v12, v12, v3
	v_add_u32_e32 v13, 0xf8, v5
	v_cmp_gt_i32_e32 vcc, 1, v10
	v_and_b32_e32 v13, 0xfc, v13
	v_add_u32_e32 v14, 0xf0, v5
	s_waitcnt lgkmcnt(0)
	v_add_f32_e32 v12, v3, v12
	v_cndmask_b32_e32 v12, v12, v3, vcc
	ds_bpermute_b32 v13, v13, v12
	v_cmp_gt_i32_e32 vcc, 2, v10
	v_and_b32_e32 v14, 0xfc, v14
	s_waitcnt lgkmcnt(0)
	v_add_f32_e32 v13, v12, v13
	v_cndmask_b32_e32 v12, v13, v12, vcc
	ds_bpermute_b32 v13, v14, v12
	v_add_u32_e32 v14, 0xe0, v5
	v_cmp_gt_i32_e32 vcc, 4, v10
	v_and_b32_e32 v14, 0xfc, v14
	s_waitcnt lgkmcnt(0)
	v_add_f32_e32 v13, v12, v13
	v_cndmask_b32_e32 v12, v13, v12, vcc
	ds_bpermute_b32 v13, v14, v12
	v_add_u32_e32 v14, 0xc0, v5
	v_cmp_gt_i32_e32 vcc, 8, v10
	v_and_b32_e32 v14, 0xfc, v14
	s_waitcnt lgkmcnt(0)
	v_add_f32_e32 v13, v12, v13
	v_cndmask_b32_e32 v12, v13, v12, vcc
	ds_bpermute_b32 v13, v14, v12
	v_bitop3_b32 v14, v5, s45, v126 bitop3:0x6c
	v_cmp_gt_i32_e32 vcc, 16, v10
	s_waitcnt lgkmcnt(0)
	v_add_f32_e32 v5, v12, v13
	v_cndmask_b32_e32 v5, v5, v12, vcc
	ds_bpermute_b32 v12, v14, v5
	v_cmp_eq_u32_e32 vcc, 63, v10
	s_waitcnt lgkmcnt(0)
	v_add_f32_e32 v12, v5, v12
	s_and_saveexec_b64 s[6:7], vcc
	v_ashrrev_i32_e32 v11, 6, v11
	v_lshl_add_u32 v11, v11, 2, 0
	v_add_u32_e32 v11, 0x1dc00, v11
	ds_write_b32 v11, v12
	s_or_b64 exec, exec, s[6:7]
	s_mov_b32 s6, s3
	s_waitcnt lgkmcnt(0)
	s_barrier
	s_and_b64 vcc, exec, s[4:5]
	s_cbranch_vccnz fxq0_nowr
	s_waitcnt vmcnt(0)
	v_readfirstlane_b32 s7, v108
	v_mov_b32_e32 v109, 0x1dc40
	v_mov_b32_e32 v108, s7
	ds_write_b32 v109, v108
fxq0_nowr:
	s_cmp_lt_i32 s6, 1
	v_mov_b32_e32 v11, 0
	v_mov_b32_e32 v13, 0
	s_cbranch_scc1 .LBB0_379
	s_add_i32 s7, 0, 0x1dc00
	v_mov_b32_e32 v13, s7
	ds_read_b32 v13, v13

; #define LAS __attribute__((address_space(3)))
; template <int li> __device__ __forceinline__ void layer_fwd(const Args& args, LAS unsigned char* lds, const int wid_s) {
;     ...
;                     LAS float* cl = (LAS float*)(lds + att::LDS_C) + 8 * tdl;
; #pragma unroll
;                     for (int e = 0; e < 8; ++e) cl[e] = (basev + v[e]) * att::LOG2E;
;                     __syncthreads();
;                     float kn2; { const unsigned* nkp = (const unsigned*)ws + 8192 + li * 2304 + 2048 + bh * 2; kn2 = __uint_as_float(nkp[0]) + __uint_as_float(nkp[1]); }
;                     int t_lo = 0;
;                     { const unsigned* nrm = (const unsigned*)ws + 8192 + li * 2304; const unsigned* nqp = nrm + (bh * 16 + qb) * 2;
;                       const float qn2 = __uint_as_float(nqp[0]) + __uint_as_float(nqp[1]);
;                       const float B2 = sqrtf(qn2 * kn2) * 1.02f; const LAS float* cl2 = (const LAS float*)(lds + att::LDS_C);
;                       const bool skip = (lnl < 4 * qb) && (2.f * B2 + (cl2[256 * qb] - cl2[64 * lnl + 63]) <= -160.f);
;                       const unsigned long long msk = __ballot(skip); t_lo = msk ? 64 - __builtin_clzll(msk) : 0; t_lo = __builtin_amdgcn_readfirstlane(t_lo); }
.LBB0_386:
	v_cmp_gt_i32_e32 vcc, 32, v10
	v_lshl_add_u32 v4, v4, 2, 0
	v_add_u32_e32 v4, 0x18800, v4
	v_cndmask_b32_e32 v5, v12, v5, vcc
	v_sub_f32_e32 v5, v5, v3
	s_waitcnt lgkmcnt(0)
	v_add_f32_e32 v5, v5, v13
	v_add_f32_e32 v5, v5, v11
	v_add_f32_e32 v5, v5, v15
	v_add_f32_e32 v5, v5, v14
	v_add_f32_e32 v5, v5, v17
	v_add_f32_e32 v5, v5, v16
	v_add_f32_e32 v16, v5, v18
	v_pk_add_f32 v[0:1], v[0:1], v[16:17] op_sel_hi:[1,0]
	v_pk_add_f32 v[2:3], v[2:3], v[16:17] op_sel_hi:[1,0]
	v_pk_mul_f32 v[12:13], v[0:1], s[24:25] op_sel_hi:[1,0]
	v_pk_add_f32 v[0:1], v[8:9], v[16:17] op_sel_hi:[1,0]
	v_pk_mul_f32 v[2:3], v[2:3], s[24:25] op_sel_hi:[1,0]
	v_pk_mul_f32 v[14:15], v[0:1], s[24:25] op_sel_hi:[1,0]
	v_pk_add_f32 v[0:1], v[6:7], v[16:17] op_sel_hi:[1,0]
	s_lshl_b32 s6, s30, 3
	v_pk_mul_f32 v[0:1], v[0:1], s[24:25] op_sel_hi:[1,0]
	ds_write_b128 v4, v[0:3] offset:16
	v_mov_b32_e32 v0, s6
	ds_write_b128 v4, v[12:15]
	s_waitcnt lgkmcnt(0)
	s_barrier
	s_sub_i32 s58, 15, s54
	s_lshl_b32 s42, s58, 2
	v_cmp_gt_i32_e32 vcc, s42, v10
	s_mov_b64 s[6:7], 0
	s_waitcnt vmcnt(0)
	v_add_f32_e32 v0, v102, v103
	s_and_saveexec_b64 s[8:9], vcc
	s_cbranch_execz .LBB0_388
	s_lshl_b32 s6, s30, 7
	s_lshl_b32 s7, s58, 3
	s_or_b32 s6, s7, s6
	v_mov_b32_e32 v1, s6
	s_lshl_b32 s6, s58, 10
	s_add_i32 s7, 0, 0x18800
	s_add_i32 s6, s7, s6
	v_lshl_add_u32 v1, v10, 8, s7
	v_mov_b32_e32 v4, s6
	ds_read_b32 v4, v4
	ds_read_b32 v1, v1 offset:252
	s_waitcnt lgkmcnt(0)
	v_sub_f32_e32 v1, v4, v1
	s_waitcnt vmcnt(0)
	v_add_f32_e32 v2, v104, v105
	v_mul_f32_e32 v2, v0, v2
	v_mul_f32_e32 v3, 0x4f800000, v2
	v_cmp_gt_f32_e32 vcc, s52, v2
	s_nop 1
	v_cndmask_b32_e32 v2, v2, v3, vcc
	v_sqrt_f32_e32 v3, v2
	s_nop 0
	v_add_u32_e32 v5, -1, v3
	v_add_u32_e32 v6, 1, v3
	v_fma_f32 v7, -v5, v3, v2
	v_fma_f32 v8, -v6, v3, v2
	v_cmp_ge_f32_e64 s[6:7], 0, v7
	s_nop 1
	v_cndmask_b32_e64 v3, v3, v5, s[6:7]
	v_cmp_lt_f32_e64 s[6:7], 0, v8
	s_nop 1
	v_cndmask_b32_e64 v3, v3, v6, s[6:7]
	v_mul_f32_e32 v5, 0x37800000, v3
	v_cndmask_b32_e32 v3, v3, v5, vcc
	v_cmp_class_f32_e32 vcc, v2, v124
	s_nop 1
	v_cndmask_b32_e32 v2, v3, v2, vcc
	v_mul_f32_e32 v2, 0x3f828f5c, v2
	v_fmac_f32_e32 v1, 2.0, v2
	v_cmp_ge_f32_e32 vcc, s53, v1
	s_and_b64 s[6:7], vcc, exec

; __device__ __forceinline__ int lane_id() { unsigned m = ~0u; asm volatile("" : "+s"(m)); return (int)__builtin_amdgcn_mbcnt_hi(m, __builtin_amdgcn_mbcnt_lo(m, 0u)); }
; #define LAS __attribute__((address_space(3)))
; template <int li> __device__ __forceinline__ void layer_fwd(const Args& args, LAS unsigned char* lds, const int wid_s) {
;     ...
;             if (fox) {
;                 unsigned* qctr = (unsigned*)ws + 24576 + j;
;                 LAS unsigned* uq = (LAS unsigned*)(lds + att::LDS_SC + 64);
;                 const float bmax = 0.f;
; #pragma unroll 1
;                 for (;;) {
;                     int zl = 0; asm volatile("" : "+v"(zl));
;                     if ((wid_s == 0) && (pg8::lane_id() == 0)) uq[zl] = atomicAdd(qctr, 1u);
;                     __syncthreads();
;                     const unsigned u = (unsigned)__builtin_amdgcn_readfirstlane((int)uq[zl]);
.LBB0_1687:
	s_or_b64 exec, exec, s[10:11]
	s_mov_b32 s10, -1
	s_waitcnt lgkmcnt(0)
	s_barrier
	s_mov_b32 s19, 0
	v_mbcnt_lo_u32_b32 v0, s10, 0
	v_mbcnt_hi_u32_b32 v0, s10, v0
	s_mov_b32 s10, s2
	s_mov_b32 s12, s19
	s_load_dwordx2 s[10:11], s[0:1], 0x88
	s_ashr_i32 s13, s12, 31
	s_mov_b32 s34, 0xfffe0000
	v_mov_b32_e32 v119, 0
	s_movk_i32 s49, 0x80
	s_waitcnt lgkmcnt(0)
	s_add_u32 s10, s10, s12
	s_addc_u32 s11, s11, s13
	s_add_u32 s14, s10, 0x200000
	s_addc_u32 s15, s11, 0
	s_add_u32 s29, s10, 0x9400000
	s_addc_u32 s40, s11, 0
	s_add_u32 s41, s10, 0xb400000
	s_addc_u32 s46, s11, 0
	s_add_u32 s47, s10, 0xd400000
	s_addc_u32 s48, s11, 0
	s_add_u32 s22, s10, 0xc800
	s_addc_u32 s23, s11, 0
	s_add_u32 s24, s10, 0xe800
	s_addc_u32 s25, s11, 0
	s_add_u32 s26, s10, 0x18004
	s_addc_u32 s27, s11, 0
	s_add_i32 s50, 0, 0x1dc00
	s_add_i32 s51, 0, 0x1dc04
	s_add_i32 s52, 0, 0x1dc08
	s_add_i32 s53, 0, 0x1dc0c
	s_add_i32 s54, 0, 0x1dc10
	s_add_i32 s55, 0, 0x1dc14
	s_add_i32 s56, 0, 0x1dc18
	s_mov_b32 s28, 0x3fb8aa3b
	s_mov_b32 s57, 0xf800000
	v_mov_b32_e32 v124, 0x260
	s_mov_b32 s58, 0xc3200000
	v_mov_b32_e32 v125, 0xc2800000
	s_mov_b64 s[30:31], 0x780000
	s_mov_b32 s35, -1
	v_bfrev_b32_e32 v126, 0.5
	s_add_i32 s59, 0, 0x18800
	s_add_i32 s66, s74, 0x2000
	s_add_i32 s67, s74, 0xa000
	s_add_i32 s90, s74, 0x4000
	s_add_i32 s91, s74, 0xc000
	v_mov_b32_e32 v127, 0xff800000
	s_and_b64 vcc, exec, s[4:5]
	s_cbranch_vccnz fxq2_pre
	s_mov_b64 s[10:11], exec
	s_mov_b64 exec, 1
	v_mov_b32_e32 v2, 1
	global_atomic_add v2, v119, v2, s[26:27] sc0
	v_mov_b32_e32 v3, 0x1dc40
	s_waitcnt vmcnt(0)
	ds_write_b32 v3, v2
	s_mov_b64 exec, s[10:11]
fxq2_pre:
	s_branch .LBB0_1690

; __device__ __forceinline__ int lane_id() { unsigned m = ~0u; asm volatile("" : "+s"(m)); return (int)__builtin_amdgcn_mbcnt_hi(m, __builtin_amdgcn_mbcnt_lo(m, 0u)); }
; #define LAS __attribute__((address_space(3)))
; template <int li> __device__ __forceinline__ void layer_fwd(const Args& args, LAS unsigned char* lds, const int wid_s) {
;     ...
;                 for (;;) {
;                     int zl = 0; asm volatile("" : "+v"(zl));
;                     if ((wid_s == 0) && (pg8::lane_id() == 0)) uq[zl] = atomicAdd(qctr, 1u);
;                     __syncthreads();
;                     const unsigned u = (unsigned)__builtin_amdgcn_readfirstlane((int)uq[zl]);
;                     if (u >= 1024u) break;
;                     const int qb = 15 - (int)(u >> 6), bh = (int)(u & 63u), b = bh >> 4, h = bh & 15;
;                     const int lnl = pg8::lane_id(); const int tdl = wid_s * 64 + lnl;
;                     const int L = 256 * (qb + 1);
;                     float v[8];
;                     if (8 * tdl < L) { const float* lf = logf_buf + (size_t)bh * SEQ + 8 * tdl; const f32x4 a = *(const f32x4*)lf, c = *(const f32x4*)(lf + 4);
;                         v[0] = a[0]; v[1] = v[0] + a[1]; v[2] = v[1] + a[2]; v[3] = v[2] + a[3]; v[4] = v[3] + c[0]; v[5] = v[4] + c[1]; v[6] = v[5] + c[2]; v[7] = v[6] + c[3]; }
;                     else {
; #pragma unroll
;                         for (int e = 0; e < 8; ++e) v[e] = 0.f; }
;                     float incl = v[7];
; #pragma unroll
;                     for (int o = 1; o < 64; o <<= 1) { const float t = __int_as_float(__builtin_amdgcn_ds_bpermute(((lnl - o) & 63) << 2, __float_as_int(incl))); if (lnl >= o) incl += t; }
;                     LAS float* wsum = (LAS float*)(lds + att::LDS_SC);
;                     if (lnl == 63) wsum[tdl >> 6] = incl;
;                     __syncthreads();
;                     float basev = incl - v[7];
.LBB0_1690:
	v_mov_b32_e32 v0, 0
	v_lshl_add_u32 v0, v0, 2, 0
	v_add_u32_e32 v0, 0x1dc40, v0
	s_waitcnt lgkmcnt(0)
	s_barrier
	ds_read_b32 v0, v0
	s_mov_b64 s[10:11], -1
	s_waitcnt lgkmcnt(0)
	v_readfirstlane_b32 s21, v0
	s_cmpk_gt_u32 s21, 0x3ff
	s_cbranch_scc1 .LBB0_1689
	s_and_b32 s12, s21, 63
	s_lshr_b32 s13, s21, 6
	s_sub_i32 s13, 15, s13
	s_lshl_b32 s13, s13, 3
	s_lshl_b32 s10, s12, 7
	s_or_b32 s13, s13, s10
	s_lshl_b32 s12, s12, 3
	v_mov_b32_e32 v106, s12
	v_mov_b32_e32 v107, s13
	s_and_b64 vcc, exec, s[4:5]
	s_cbranch_vccnz fxq2_noq
	s_mov_b64 s[10:11], exec
	s_mov_b64 exec, 1
	v_mov_b32_e32 v108, 1
	global_atomic_add v108, v119, v108, s[26:27] sc0
	s_mov_b64 exec, s[10:11]
fxq2_noq:
	global_load_dwordx2 v[102:103], v106, s[24:25]
	global_load_dwordx2 v[104:105], v107, s[22:23]
	s_mov_b32 s10, -1
	s_lshr_b32 s43, s21, 6
	v_mbcnt_lo_u32_b32 v0, s10, 0
	v_mbcnt_hi_u32_b32 v10, s10, v0
	v_add_u32_e32 v11, s77, v10
	s_lshl_b32 s10, s43, 8
	s_sub_i32 s10, 0x1000, s10
	v_lshlrev_b32_e32 v4, 3, v11
	v_mov_b32_e32 v0, 0
	s_and_b32 s36, s21, 63
	v_cmp_gt_i32_e32 vcc, s10, v4
	v_mov_b32_e32 v1, v0
	v_mov_b32_e32 v8, v0
	v_mov_b32_e32 v9, v0
	v_mov_b32_e32 v6, v0
	v_mov_b32_e32 v7, v0
	v_mov_b32_e32 v2, v0
	v_mov_b32_e32 v3, v0
	s_and_saveexec_b64 s[10:11], vcc
	s_cbranch_execz .LBB0_1699
	s_lshl_b32 s12, s36, 14
	s_add_u32 s12, s14, s12
	s_addc_u32 s13, s15, 0
	v_ashrrev_i32_e32 v5, 31, v4
	v_lshl_add_u64 v[6:7], v[4:5], 2, s[12:13]
	global_load_dwordx4 v[0:3], v[6:7], off
	global_load_dwordx4 v[12:15], v[6:7], off offset:16
	s_waitcnt vmcnt(1)
	v_add_f32_e32 v1, v0, v1
	v_add_f32_e32 v8, v2, v1
	v_add_f32_e32 v9, v3, v8
	s_waitcnt vmcnt(0)
	v_add_f32_e32 v6, v12, v9
	v_add_f32_e32 v7, v13, v6
	v_add_f32_e32 v2, v14, v7
	v_add_f32_e32 v3, v15, v2
.LBB0_1699:
	s_or_b64 exec, exec, s[10:11]
	v_lshlrev_b32_e32 v5, 2, v10
	v_add_u32_e32 v12, 0xfc, v5
	v_and_b32_e32 v12, 0xfc, v12
	ds_bpermute_b32 v12, v12, v3
	v_add_u32_e32 v13, 0xf8, v5
	v_cmp_gt_i32_e32 vcc, 1, v10
	v_and_b32_e32 v13, 0xfc, v13
	v_add_u32_e32 v14, 0xf0, v5
	s_waitcnt lgkmcnt(0)
	v_add_f32_e32 v12, v3, v12
	v_cndmask_b32_e32 v12, v12, v3, vcc
	ds_bpermute_b32 v13, v13, v12
	v_cmp_gt_i32_e32 vcc, 2, v10
	v_and_b32_e32 v14, 0xfc, v14
	s_waitcnt lgkmcnt(0)
	v_add_f32_e32 v13, v12, v13
	v_cndmask_b32_e32 v12, v13, v12, vcc
	ds_bpermute_b32 v13, v14, v12
	v_add_u32_e32 v14, 0xe0, v5
	v_cmp_gt_i32_e32 vcc, 4, v10
	v_and_b32_e32 v14, 0xfc, v14
	s_waitcnt lgkmcnt(0)
	v_add_f32_e32 v13, v12, v13
	v_cndmask_b32_e32 v12, v13, v12, vcc
	ds_bpermute_b32 v13, v14, v12
	v_add_u32_e32 v14, 0xc0, v5
	v_cmp_gt_i32_e32 vcc, 8, v10
	v_and_b32_e32 v14, 0xfc, v14
	s_waitcnt lgkmcnt(0)
	v_add_f32_e32 v13, v12, v13
	v_cndmask_b32_e32 v12, v13, v12, vcc
	ds_bpermute_b32 v13, v14, v12
	v_bitop3_b32 v14, v5, s49, v126 bitop3:0x6c
	v_cmp_gt_i32_e32 vcc, 16, v10
	s_waitcnt lgkmcnt(0)
	v_add_f32_e32 v5, v12, v13
	v_cndmask_b32_e32 v5, v5, v12, vcc
	ds_bpermute_b32 v12, v14, v5
	v_cmp_eq_u32_e32 vcc, 63, v10
	s_waitcnt lgkmcnt(0)
	v_add_f32_e32 v12, v5, v12
	s_and_saveexec_b64 s[10:11], vcc
	v_ashrrev_i32_e32 v11, 6, v11
	v_lshl_add_u32 v11, v11, 2, 0
	v_add_u32_e32 v11, 0x1dc00, v11
	ds_write_b32 v11, v12
	s_or_b64 exec, exec, s[10:11]
	s_mov_b32 s10, s3
	s_waitcnt lgkmcnt(0)
	s_barrier
	s_and_b64 vcc, exec, s[4:5]
	s_cbranch_vccnz fxq2_nowr
	s_waitcnt vmcnt(0)
	v_readfirstlane_b32 s11, v108
	v_mov_b32_e32 v109, 0x1dc40
	v_mov_b32_e32 v108, s11
	ds_write_b32 v109, v108
fxq2_nowr:
	s_cmp_lt_i32 s10, 1
	v_mov_b32_e32 v11, 0
	v_mov_b32_e32 v13, 0
	s_cbranch_scc1 .LBB0_1703
	v_mov_b32_e32 v13, s50
	ds_read_b32 v13, v13

; #define LAS __attribute__((address_space(3)))
; template <int li> __device__ __forceinline__ void layer_fwd(const Args& args, LAS unsigned char* lds, const int wid_s) {
;     ...
;                     LAS float* cl = (LAS float*)(lds + att::LDS_C) + 8 * tdl;
; #pragma unroll
;                     for (int e = 0; e < 8; ++e) cl[e] = (basev + v[e]) * att::LOG2E;
;                     __syncthreads();
;                     float kn2; { const unsigned* nkp = (const unsigned*)ws + 8192 + li * 2304 + 2048 + bh * 2; kn2 = __uint_as_float(nkp[0]) + __uint_as_float(nkp[1]); }
;                     int t_lo = 0;
;                     { const unsigned* nrm = (const unsigned*)ws + 8192 + li * 2304; const unsigned* nqp = nrm + (bh * 16 + qb) * 2;
;                       const float qn2 = __uint_as_float(nqp[0]) + __uint_as_float(nqp[1]);
;                       const float B2 = sqrtf(qn2 * kn2) * 1.02f; const LAS float* cl2 = (const LAS float*)(lds + att::LDS_C);
;                       const bool skip = (lnl < 4 * qb) && (2.f * B2 + (cl2[256 * qb] - cl2[64 * lnl + 63]) <= -160.f);
;                       const unsigned long long msk = __ballot(skip); t_lo = msk ? 64 - __builtin_clzll(msk) : 0; t_lo = __builtin_amdgcn_readfirstlane(t_lo); }
.LBB0_1710:
	v_cmp_gt_i32_e32 vcc, 32, v10
	v_lshl_add_u32 v4, v4, 2, 0
	v_add_u32_e32 v4, 0x18800, v4
	v_cndmask_b32_e32 v5, v12, v5, vcc
	v_sub_f32_e32 v5, v5, v3
	s_waitcnt lgkmcnt(0)
	v_add_f32_e32 v5, v5, v13
	v_add_f32_e32 v5, v5, v11
	v_add_f32_e32 v5, v5, v15
	v_add_f32_e32 v5, v5, v14
	v_add_f32_e32 v5, v5, v17
	v_add_f32_e32 v5, v5, v16
	v_add_f32_e32 v16, v5, v18
	v_pk_add_f32 v[0:1], v[0:1], v[16:17] op_sel_hi:[1,0]
	v_pk_add_f32 v[2:3], v[2:3], v[16:17] op_sel_hi:[1,0]
	v_pk_mul_f32 v[12:13], v[0:1], s[28:29] op_sel_hi:[1,0]
	v_pk_add_f32 v[0:1], v[8:9], v[16:17] op_sel_hi:[1,0]
	v_pk_mul_f32 v[2:3], v[2:3], s[28:29] op_sel_hi:[1,0]
	v_pk_mul_f32 v[14:15], v[0:1], s[28:29] op_sel_hi:[1,0]
	v_pk_add_f32 v[0:1], v[6:7], v[16:17] op_sel_hi:[1,0]
	s_lshl_b32 s10, s36, 3
	v_pk_mul_f32 v[0:1], v[0:1], s[28:29] op_sel_hi:[1,0]
	ds_write_b128 v4, v[0:3] offset:16
	v_mov_b32_e32 v0, s10
	ds_write_b128 v4, v[12:15]
	s_waitcnt lgkmcnt(0)
	s_barrier
	s_sub_i32 s61, 15, s43
	s_lshl_b32 s42, s61, 2
	v_cmp_gt_i32_e32 vcc, s42, v10
	s_mov_b64 s[10:11], 0
	s_waitcnt vmcnt(0)
	v_add_f32_e32 v0, v102, v103
	s_and_saveexec_b64 s[12:13], vcc
	s_cbranch_execz .LBB0_1712
	s_lshl_b32 s10, s36, 7
	s_lshl_b32 s11, s61, 3
	s_or_b32 s10, s11, s10
	v_mov_b32_e32 v1, s10
	s_lshl_b32 s10, s61, 10
	s_add_i32 s10, s59, s10
	v_lshl_add_u32 v1, v10, 8, s59
	v_mov_b32_e32 v4, s10
	ds_read_b32 v4, v4
	ds_read_b32 v1, v1 offset:252
	s_waitcnt lgkmcnt(0)
	v_sub_f32_e32 v1, v4, v1
	s_waitcnt vmcnt(0)
	v_add_f32_e32 v2, v104, v105
	v_mul_f32_e32 v2, v0, v2
	v_mul_f32_e32 v3, 0x4f800000, v2
	v_cmp_gt_f32_e32 vcc, s57, v2
	s_nop 1
	v_cndmask_b32_e32 v2, v2, v3, vcc
	v_sqrt_f32_e32 v3, v2
	s_nop 0
	v_add_u32_e32 v5, -1, v3
	v_add_u32_e32 v6, 1, v3
	v_fma_f32 v7, -v5, v3, v2
	v_fma_f32 v8, -v6, v3, v2
	v_cmp_ge_f32_e64 s[10:11], 0, v7
	s_nop 1
	v_cndmask_b32_e64 v3, v3, v5, s[10:11]
	v_cmp_lt_f32_e64 s[10:11], 0, v8
	s_nop 1
	v_cndmask_b32_e64 v3, v3, v6, s[10:11]
	v_mul_f32_e32 v5, 0x37800000, v3
	v_cndmask_b32_e32 v3, v3, v5, vcc
	v_cmp_class_f32_e32 vcc, v2, v124
	s_nop 1
	v_cndmask_b32_e32 v2, v3, v2, vcc
	v_mul_f32_e32 v2, 0x3f828f5c, v2
	v_fmac_f32_e32 v1, 2.0, v2
	v_cmp_ge_f32_e32 vcc, s58, v1
	s_and_b64 s[10:11], vcc, exec
